# phase 0 sheds the 256 layer-1 w_out transposes (9 items per workgroup instead of 10); they run on workgroups 32.. after their layer-0 latent post tiles while the context out-projection finishes
# baseline (speedup 1.0000x reference)
; #define ITEM_BEGIN { size_t z_ = 0; asm volatile("" : "+s"(z_)); q.ws = p.ws + z_; sm = smem + osgpr(0); }
; #define PHASE_BEGIN P q = p; { size_t z_ = 0; asm volatile("" : "+s"(z_)); q.ws = p.ws + z_; } unsigned char* sm = smem + osgpr(0); const int b1 = osgpr(bid); (void)sm; (void)b1;
; DI void weight_prep_item(const P& q, int l, int it, unsigned char* sm) {
;     if (it < 96) adaln_item(q, l * 96 + it, sm);
;     else if (it < 96 + 896) { const int r = it - 96, kt = r / 28, nt = r % 28;
;         const int n0 = nt * 256, srcoff = n0 < 1024 ? 0 : (n0 < 3072 ? 32 : 48);
;         transpose_item(q.w_in + (size_t)l * DM * INW, INW, srcoff, (bf16_t*)(q.ws + WS_WINT) + (size_t)l * NP * DM, kt, nt, sm); }
;     else if (it < 96 + 896 + 256) { const int r = it - 96 - 896, kt = r / 8, nt = r % 8;
;         transpose_item(q.w_out + (size_t)l * DM * DM, DM, 0, (bf16_t*)(q.ws + WS_WOUTT) + (size_t)l * DM * DM, kt, nt, sm); }
;     else { const int kt = it - 96 - 896 - 256;
;         narrow_item(q.w_in + (size_t)l * DM * INW, (bf16_t*)(q.ws + WS_WNT) + (size_t)l * NNAR * DM, kt); }
; }
; __global__ __launch_bounds__(512, 2) void mega(P p) {
;     ...
;     for (int rep = 0; rep < REP_P0; ++rep) {
;         PHASE_BEGIN
;         for (int it = b1; it < 2560; it += nb) { ITEM_BEGIN weight_prep_item(q, it & 1, it >> 1, sm); }
.LBB0_17:
	s_mov_b64 s[6:7], 0
	s_mov_b32 s6, 0
	v_readlane_b32 s30, v253, 0
	s_cmpk_gt_i32 s30, 0x9ff
	s_mov_b32 s7, 0
	s_cbranch_scc1 .LBB0_42
	s_load_dwordx4 s[8:11], s[0:1], 0x18
	s_load_dwordx2 s[16:17], s[0:1], 0x8
	s_load_dwordx2 s[18:19], s[0:1], 0x28
	s_load_dwordx4 s[12:15], s[0:1], 0x40
	s_mov_b32 s31, 0x2aaaaaab
	s_waitcnt lgkmcnt(0)
	v_writelane_b32 v252, s14, 16
	v_writelane_b32 v252, s15, 17
	s_add_u32 s34, s10, 0xb40000
	s_addc_u32 s35, s11, 0
	v_mov_b32_e32 v77, 0
	s_movk_i32 s36, 0x70c0
	s_movk_i32 s37, 0x404
	s_mov_b64 s[10:11], 0x3800000
	s_mov_b32 s38, 0x3800000
	s_movk_i32 s39, 0x27ff
	s_movk_i32 s40, 0x2000
	s_mov_b64 s[20:21], 0x800
	s_movk_i32 s41, 0x25ff
	s_movk_i32 s42, 0x6000
	s_mov_b32 s43, 0xff4c0000
	s_mov_b32 s44, 0xff580000
	s_mov_b32 s45, 0xff640000
	s_mov_b32 s46, 0xff700000
	s_mov_b32 s47, 0xff7c0000
	s_mov_b32 s48, 0xff880000
	s_mov_b32 s49, 0xff940000
	s_mov_b32 s51, 0xffa00000
	s_mov_b32 s52, 0xffac0000
	s_mov_b32 s53, 0xffb80000
	s_mov_b32 s54, 0xffc40000
	s_mov_b32 s55, 0xffd00000
	s_mov_b32 s56, 0xffdc0000
	s_mov_b32 s57, 0xffe80000
	s_mov_b32 s58, 0xfff40000
	s_mov_b64 s[22:23], 0xc00000
	s_movk_i32 s59, 0x500
	s_movk_i32 s60, 0x140
	s_movk_i32 s61, 0x1800
	v_mov_b32_e32 v97, 0xc00
	v_mov_b32_e32 v167, 0x400
	v_mov_b32_e32 v99, 0x3000000
	s_branch .LBB0_21

; DI int otid() { int t = threadIdx.x; asm volatile("" : "+v"(t)); return t; }
; #define ITEM_BEGIN { size_t z_ = 0; asm volatile("" : "+s"(z_)); q.ws = p.ws + z_; sm = smem + osgpr(0); }
; #define PHASE_BEGIN P q = p; { size_t z_ = 0; asm volatile("" : "+s"(z_)); q.ws = p.ws + z_; } unsigned char* sm = smem + osgpr(0); const int b1 = osgpr(bid); (void)sm; (void)b1;
; DI void narrow_item(const float* src, bf16_t* dst, int kt) {
;     const int tid = otid();
; #pragma unroll
;     for (int j = 0; j < 6; ++j) {
;         const int e = tid + 512 * j, kr = e / 48, cn = e % 48;
;         const int sc = cn < 32 ? 1024 + cn : 3104 + (cn - 32);
;         dst[(size_t)cn * 2048 + kt * 64 + kr] = f2bf(src[(size_t)(kt * 64 + kr) * INW + sc]);
;     }
; }
; __global__ __launch_bounds__(512, 2) void mega(P p) {
;     ...
;     for (int rep = 0; rep < REP_P0; ++rep) {
;         PHASE_BEGIN
;         for (int it = b1; it < 2560; it += nb) { ITEM_BEGIN weight_prep_item(q, it & 1, it >> 1, sm); }
.LBB0_21:
	s_mov_b32 s98, s30
	s_cmpk_lt_i32 s30, 0x700
	s_cbranch_scc1 .Lp0_go
	s_lshr_b32 s99, s30, 8
	s_and_b32 s100, s30, 0xff
	s_lshr_b32 s100, s100, 1
	s_bitcmp1_b32 s30, 0
	s_cbranch_scc1 .Lp0_odd
	s_cmp_eq_u32 s99, 9
	s_cbranch_scc1 .LBB0_20
	s_branch .Lp0_go
.Lp0_odd:
	s_cmpk_lt_u32 s100, 0x60
	s_cbranch_scc0 .Lp0_odd_hi
	s_cmp_eq_u32 s99, 9
	s_cbranch_scc1 .LBB0_20
	s_cmp_eq_u32 s99, 8
	s_cbranch_scc0 .Lp0_go
	s_add_i32 s98, s30, 0xff
	s_branch .Lp0_go
.Lp0_odd_hi:
	s_cmp_eq_u32 s99, 8
	s_cbranch_scc1 .LBB0_20
	s_cmp_eq_u32 s99, 7
	s_cbranch_scc0 .Lp0_go
	s_add_i32 s98, s30, 0x1ff
.Lp0_go:
	s_mov_b64 s[24:25], 0
	s_add_u32 s24, s68, s24
	s_mov_b32 s6, 0
	s_addc_u32 s25, s69, s25
	s_add_i32 s62, s6, 0
	s_and_b32 s63, s98, 1
	s_ashr_i32 s64, s98, 1
	s_cmpk_gt_i32 s64, 0x5f
	s_mov_b64 s[26:27], -1
	s_cbranch_scc0 .LBB0_31
	s_cmpk_gt_u32 s64, 0x3df
	s_cbranch_scc0 .LBB0_28
	s_cmpk_gt_u32 s64, 0x4df
	s_cbranch_scc0 .LBB0_25
	v_mov_b32_e32 v1, v166
	s_mul_i32 s6, s63, 0x3860000
	v_mul_hi_i32 v0, v1, s31
	v_lshrrev_b32_e32 v2, 31, v0
	v_ashrrev_i32_e32 v0, 3, v0
	s_add_u32 s26, s12, s6
	v_add_u32_e32 v0, v0, v2
	s_addc_u32 s27, s13, 0
	s_mul_i32 s6, s63, 0x30000
	v_mul_lo_u32 v2, v0, 48
	s_add_u32 s28, s24, s6
	v_sub_u32_e32 v2, v1, v2
	s_addc_u32 s29, s25, 0
	s_lshl_b32 s6, s64, 6
	v_cmp_gt_i32_e32 vcc, 32, v2
	s_add_i32 s6, s6, 0xfffec800
	v_mov_b64_e32 v[4:5], s[26:27]
	v_cndmask_b32_e32 v3, v97, v167, vcc
	v_add_u32_e32 v76, v3, v2
	v_add_u32_e32 v3, s6, v0
	v_mad_i64_i32 v[6:7], s[26:27], v3, s36, v[4:5]
	v_add_u32_e32 v3, 0x200, v1
	v_mul_hi_i32 v8, v3, s31
	v_lshrrev_b32_e32 v9, 31, v8
	v_ashrrev_i32_e32 v8, 3, v8
	v_add_u32_e32 v8, v8, v9
	v_mul_lo_u32 v9, v8, 48
	v_sub_u32_e32 v10, v3, v9
	v_cmp_gt_i32_e32 vcc, 32, v10
	v_lshl_add_u64 v[6:7], v[76:77], 2, v[6:7]
	s_nop 0
	v_cndmask_b32_e32 v3, v97, v167, vcc
	v_add_u32_e32 v76, v3, v10
	v_add_u32_e32 v3, s6, v8
	v_mad_i64_i32 v[12:13], s[26:27], v3, s36, v[4:5]
	v_add_u32_e32 v3, 0x400, v1
	v_mul_hi_i32 v9, v3, s31
	v_lshrrev_b32_e32 v11, 31, v9
	v_ashrrev_i32_e32 v9, 3, v9
	v_add_u32_e32 v14, v9, v11
	v_mul_lo_u32 v9, v14, 48
	v_sub_u32_e32 v16, v3, v9
	v_cmp_gt_i32_e32 vcc, 32, v16
	v_lshl_add_u64 v[12:13], v[76:77], 2, v[12:13]
	v_add_u32_e32 v9, 0x600, v1
	v_cndmask_b32_e32 v3, v97, v167, vcc
	v_add_u32_e32 v76, v3, v16
	v_add_u32_e32 v3, s6, v14
	v_mad_i64_i32 v[18:19], s[26:27], v3, s36, v[4:5]
	v_lshl_add_u64 v[18:19], v[76:77], 2, v[18:19]
	global_load_dword v3, v[6:7], off
	s_nop 0
	global_load_dword v7, v[12:13], off
	s_nop 0
	global_load_dword v13, v[18:19], off
	v_mul_hi_i32 v6, v9, s31
	v_lshrrev_b32_e32 v11, 31, v6
	v_ashrrev_i32_e32 v6, 3, v6
	v_add_u32_e32 v6, v6, v11
	v_mul_lo_u32 v11, v6, 48
	v_sub_u32_e32 v12, v9, v11
	v_cmp_gt_i32_e32 vcc, 32, v12
	v_ashrrev_i32_e32 v17, 31, v16
	s_nop 0
	v_cndmask_b32_e32 v9, v97, v167, vcc
	v_add_u32_e32 v76, v9, v12
	v_add_u32_e32 v9, s6, v6
	v_mad_i64_i32 v[18:19], s[26:27], v9, s36, v[4:5]
	v_add_u32_e32 v9, 0x800, v1
	v_mul_hi_i32 v11, v9, s31
	v_lshrrev_b32_e32 v15, 31, v11
	v_ashrrev_i32_e32 v11, 3, v11
	v_add_u32_e32 v20, v11, v15
	v_mul_lo_u32 v11, v20, 48
	v_sub_u32_e32 v22, v9, v11
	v_cmp_gt_i32_e32 vcc, 32, v22
	v_lshl_add_u64 v[18:19], v[76:77], 2, v[18:19]
	v_add_u32_e32 v1, 0xa00, v1
	v_cndmask_b32_e32 v9, v97, v167, vcc
	v_add_u32_e32 v76, v9, v22
	v_add_u32_e32 v9, s6, v20
	v_mad_i64_i32 v[24:25], s[26:27], v9, s36, v[4:5]
	v_mul_hi_i32 v9, v1, s31
	v_lshrrev_b32_e32 v11, 31, v9
	v_ashrrev_i32_e32 v9, 3, v9
	v_lshl_add_u64 v[24:25], v[76:77], 2, v[24:25]
	global_load_dword v19, v[18:19], off
	s_nop 0
	global_load_dword v21, v[24:25], off
	v_add_u32_e32 v18, v9, v11
	v_mul_lo_u32 v9, v18, 48
	v_sub_u32_e32 v24, v1, v9
	v_cmp_gt_i32_e32 vcc, 32, v24
	v_ashrrev_i32_e32 v11, 31, v10
	v_ashrrev_i32_e32 v9, 31, v8
	v_cndmask_b32_e32 v1, v97, v167, vcc
	v_add_u32_e32 v76, v1, v24
	v_add_u32_e32 v1, s6, v18
	v_mad_i64_i32 v[4:5], s[26:27], v1, s36, v[4:5]
	v_lshl_add_u64 v[4:5], v[76:77], 2, v[4:5]
	global_load_dword v4, v[4:5], off
	s_lshl_b64 s[26:27], s[6:7], 1
	s_add_u32 s6, s28, s26
	s_addc_u32 s27, s29, s27
	s_add_u32 s26, s6, 0x17e4d200
	s_addc_u32 s27, s27, 0
	v_ashrrev_i32_e32 v1, 31, v0
	v_ashrrev_i32_e32 v15, 31, v14
	v_ashrrev_i32_e32 v23, 31, v22
	v_ashrrev_i32_e32 v25, 31, v24
	s_waitcnt vmcnt(5)
	v_cvt_pk_bf16_f32 v5, v3, s0
	v_ashrrev_i32_e32 v3, 31, v2
	v_lshlrev_b64 v[2:3], 12, v[2:3]
	v_lshl_add_u64 v[2:3], s[26:27], 0, v[2:3]
	v_lshl_add_u64 v[0:1], v[0:1], 1, v[2:3]
	global_store_short v[0:1], v5, off
	v_lshlrev_b64 v[0:1], 12, v[10:11]
	v_lshl_add_u64 v[0:1], s[26:27], 0, v[0:1]
	s_waitcnt vmcnt(5)
	v_cvt_pk_bf16_f32 v2, v7, s0
	v_lshl_add_u64 v[0:1], v[8:9], 1, v[0:1]
	global_store_short v[0:1], v2, off
	v_lshlrev_b64 v[0:1], 12, v[16:17]
	v_lshl_add_u64 v[0:1], s[26:27], 0, v[0:1]
	s_waitcnt vmcnt(5)
	v_cvt_pk_bf16_f32 v2, v13, s0
	v_lshl_add_u64 v[0:1], v[14:15], 1, v[0:1]
	v_ashrrev_i32_e32 v13, 31, v12
	global_store_short v[0:1], v2, off
	v_lshlrev_b64 v[0:1], 12, v[12:13]
	v_ashrrev_i32_e32 v7, 31, v6
	v_lshl_add_u64 v[0:1], s[26:27], 0, v[0:1]
	v_lshl_add_u64 v[0:1], v[6:7], 1, v[0:1]
	s_waitcnt vmcnt(5)
	v_cvt_pk_bf16_f32 v2, v19, s0
	global_store_short v[0:1], v2, off
	v_lshlrev_b64 v[0:1], 12, v[22:23]
	s_waitcnt vmcnt(5)
	v_cvt_pk_bf16_f32 v2, v21, s0
	v_ashrrev_i32_e32 v21, 31, v20
	v_lshl_add_u64 v[0:1], s[26:27], 0, v[0:1]
	v_lshl_add_u64 v[0:1], v[20:21], 1, v[0:1]
	global_store_short v[0:1], v2, off
	v_lshlrev_b64 v[0:1], 12, v[24:25]
	v_ashrrev_i32_e32 v19, 31, v18
	v_lshl_add_u64 v[0:1], s[26:27], 0, v[0:1]
	v_lshl_add_u64 v[0:1], v[18:19], 1, v[0:1]
	s_mov_b64 s[26:27], 0
	s_waitcnt vmcnt(5)
	v_cvt_pk_bf16_f32 v2, v4, s0
	global_store_short v[0:1], v2, off

; DI u32x4 pack8(const float* o) { u32x4 r; r.x = pk2(o[0], o[1]); r.y = pk2(o[2], o[3]); r.z = pk2(o[4], o[5]); r.w = pk2(o[6], o[7]); return r; }
; DI int otid() { int t = threadIdx.x; asm volatile("" : "+v"(t)); return t; }
; DI void transpose_item(const float* src, int ld, int srcoff, bf16_t* dst, int kt, int nt, unsigned char* smem) {
;     float* tile = (float*)smem;
;     const int tid = otid();
; #pragma unroll
;     for (int i = 0; i < 8; ++i) {
;         const int kr = (tid >> 6) + 8 * i, nc = (tid & 63) * 4;
;         const f32x4 v = __builtin_nontemporal_load((const f32x4*)(src + (size_t)(kt * 64 + kr) * ld + srcoff + nt * 256 + nc));
;         tile[kr * 257 + nc + 0] = v[0]; tile[kr * 257 + nc + 1] = v[1]; tile[kr * 257 + nc + 2] = v[2]; tile[kr * 257 + nc + 3] = v[3];
;     }
;     __syncthreads();
;     {
;         const int n = tid >> 1, k0 = (tid & 1) * 32;
; #pragma unroll
;         for (int k8 = 0; k8 < 4; ++k8) {
;             float o[8];
; #pragma unroll
;             for (int j = 0; j < 8; ++j) o[j] = tile[(k0 + 8 * k8 + j) * 257 + n];
;             *(u32x4*)(dst + (size_t)(nt * 256 + n) * 2048 + kt * 64 + k0 + 8 * k8) = pack8(o);
;         }
;     }
;     __syncthreads();
; }
; DI void weight_prep_item(const P& q, int l, int it, unsigned char* sm) {
;     ...
;     else if (it < 96 + 896) { const int r = it - 96, kt = r / 28, nt = r % 28;
;         const int n0 = nt * 256, srcoff = n0 < 1024 ? 0 : (n0 < 3072 ? 32 : 48);
;         transpose_item(q.w_in + (size_t)l * DM * INW, INW, srcoff, (bf16_t*)(q.ws + WS_WINT) + (size_t)l * NP * DM, kt, nt, sm); }
.LBB0_28:
	s_andn2_b64 vcc, exec, s[26:27]
	s_cbranch_vccnz .LBB0_30
	s_lshr_b32 s6, s98, 1
	s_add_i32 s6, s6, 0xffa0
	s_bfe_u32 s26, s6, 0xe0002
	s_mulk_i32 s26, 0x4925
	s_lshr_b32 s65, s26, 17
	s_mul_i32 s26, s65, 28
	s_sub_i32 s6, s6, s26
	s_and_b32 s28, s6, 0xffff
	s_mul_i32 s26, s63, 0x3860000
	s_add_u32 s29, s12, s26
	s_addc_u32 s66, s13, 0
	s_mul_i32 s26, s63, 0x1c00000
	s_add_u32 s26, s24, s26
	s_addc_u32 s27, s25, 0
	s_cmp_lt_u32 s28, 12
	s_cselect_b32 s67, 32, 48
	s_cmp_gt_u32 s28, 3
	s_cselect_b32 s28, s67, 0
	s_lshl_b32 s28, s28, 2
	s_add_u32 s28, s29, s28
	s_addc_u32 s29, s66, 0
	s_lshl_b32 s6, s6, 8
	s_and_b32 s6, s6, 0xff00
	v_mov_b32_e32 v32, v166
	s_lshl_b32 s66, s6, 2
	s_add_u32 s28, s28, s66
	v_ashrrev_i32_e32 v33, 6, v32
	v_lshlrev_b32_e32 v0, 4, v32
	s_addc_u32 s29, s29, 0
	v_and_b32_e32 v76, 0x3f0, v0
	v_lshl_add_u32 v30, s65, 6, v33
	v_lshl_add_u64 v[28:29], s[28:29], 0, v[76:77]
	v_add_u32_e32 v2, 8, v30
	v_add_u32_e32 v8, 16, v30
	v_add_u32_e32 v10, 24, v30
	v_add_u32_e32 v16, 32, v30
	v_add_u32_e32 v18, 40, v30
	v_mad_i64_i32 v[0:1], s[28:29], v30, s36, v[28:29]
	v_mad_i64_i32 v[4:5], s[28:29], v2, s36, v[28:29]
	v_mad_i64_i32 v[8:9], s[28:29], v8, s36, v[28:29]
	v_mad_i64_i32 v[12:13], s[28:29], v10, s36, v[28:29]
	v_mad_i64_i32 v[16:17], s[28:29], v16, s36, v[28:29]
	v_mad_i64_i32 v[20:21], s[28:29], v18, s36, v[28:29]
	global_load_dwordx4 v[0:3], v[0:1], off nt
	s_nop 0
	global_load_dwordx4 v[4:7], v[4:5], off nt
	s_nop 0
	global_load_dwordx4 v[8:11], v[8:9], off nt
	s_nop 0
	global_load_dwordx4 v[12:15], v[12:13], off nt
	s_nop 0
	global_load_dwordx4 v[16:19], v[16:17], off nt
	s_nop 0
	global_load_dwordx4 v[20:23], v[20:21], off nt
	v_add_u32_e32 v24, 48, v30
	v_mad_i64_i32 v[24:25], s[28:29], v24, s36, v[28:29]
	global_load_dwordx4 v[24:27], v[24:25], off nt
	v_add_u32_e32 v30, 56, v30
	v_mad_i64_i32 v[28:29], s[28:29], v30, s36, v[28:29]
	global_load_dwordx4 v[28:31], v[28:29], off nt
	v_ashrrev_i32_e32 v34, 1, v32
	v_lshlrev_b32_e32 v32, 5, v32
	v_mul_lo_u32 v33, v33, s37
	v_and_b32_e32 v35, 32, v32
	v_add3_u32 v36, s62, v33, v76
	v_add_u32_e32 v37, 0x2020, v36
	v_add_u32_e32 v38, 0x2028, v36
	v_add_u32_e32 v39, 0x4040, v36
	v_add_u32_e32 v40, 0x4048, v36
	v_add_u32_e32 v41, 0x6060, v36
	v_add_u32_e32 v42, 0x6068, v36
	v_add_u32_e32 v43, 0x8080, v36
	v_add_u32_e32 v44, 0x8088, v36
	v_add_u32_e32 v45, 0xa0a0, v36
	v_add_u32_e32 v46, 0xa0a8, v36
	v_add_u32_e32 v47, 0xc0c0, v36
	v_add_u32_e32 v48, 0xc0c8, v36
	v_add_u32_e32 v49, 0xe0e0, v36
	v_add_u32_e32 v50, 0xe0e8, v36
	v_add_u32_e32 v32, s6, v34
	v_ashrrev_i32_e32 v33, 31, v32
	v_lshlrev_b64 v[32:33], 12, v[32:33]
	s_lshl_b32 s6, s65, 7
	v_lshlrev_b32_e32 v76, 1, v35
	s_waitcnt vmcnt(7)
	ds_write2_b32 v36, v0, v1 offset1:1
	ds_write2_b32 v36, v2, v3 offset0:2 offset1:3
	s_waitcnt vmcnt(6)
	ds_write2_b32 v37, v4, v5 offset1:1
	ds_write2_b32 v38, v6, v7 offset1:1
	s_waitcnt vmcnt(5)
	ds_write2_b32 v39, v8, v9 offset1:1
	ds_write2_b32 v40, v10, v11 offset1:1
	s_waitcnt vmcnt(4)
	ds_write2_b32 v41, v12, v13 offset1:1
	ds_write2_b32 v42, v14, v15 offset1:1
	s_waitcnt vmcnt(3)
	ds_write2_b32 v43, v16, v17 offset1:1
	ds_write2_b32 v44, v18, v19 offset1:1
	s_waitcnt vmcnt(2)
	ds_write2_b32 v45, v20, v21 offset1:1
	ds_write2_b32 v46, v22, v23 offset1:1
	s_waitcnt vmcnt(1)
	ds_write2_b32 v47, v24, v25 offset1:1
	ds_write2_b32 v48, v26, v27 offset1:1
	s_waitcnt vmcnt(0)
	ds_write2_b32 v49, v28, v29 offset1:1
	ds_write2_b32 v50, v30, v31 offset1:1
	v_mul_u32_u24_e32 v2, 0x404, v35
	v_lshlrev_b32_e32 v3, 2, v34
	v_add3_u32 v6, s62, v2, v3
	s_waitcnt lgkmcnt(0)
	s_barrier
	ds_read_b32 v2, v6
	ds_read_b32 v3, v6 offset:1028
	ds_read_b32 v7, v6 offset:2056
	ds_read_b32 v8, v6 offset:3084
	ds_read_b32 v9, v6 offset:4112
	ds_read_b32 v10, v6 offset:5140
	ds_read_b32 v11, v6 offset:6168
	ds_read_b32 v12, v6 offset:7196
	v_lshl_add_u64 v[0:1], s[26:27], 0, v[32:33]
	v_lshl_add_u64 v[0:1], v[0:1], 0, s[6:7]
	v_lshl_add_u64 v[4:5], v[0:1], 0, v[76:77]
	s_waitcnt lgkmcnt(6)
	v_cvt_pk_bf16_f32 v0, v2, v3
	s_waitcnt lgkmcnt(4)
	v_cvt_pk_bf16_f32 v1, v7, v8
	s_waitcnt lgkmcnt(2)
	v_cvt_pk_bf16_f32 v2, v9, v10
	s_waitcnt lgkmcnt(0)
	v_cvt_pk_bf16_f32 v3, v11, v12
	ds_read_b32 v7, v6 offset:8224
	ds_read_b32 v8, v6 offset:9252
	ds_read_b32 v9, v6 offset:10280
	ds_read_b32 v10, v6 offset:11308
	ds_read_b32 v11, v6 offset:12336
	ds_read_b32 v12, v6 offset:13364
	ds_read_b32 v13, v6 offset:14392
	ds_read_b32 v14, v6 offset:15420
	global_store_dwordx4 v[4:5], v[0:3], off
	s_waitcnt lgkmcnt(6)
	s_nop 0
	v_cvt_pk_bf16_f32 v0, v7, v8
	s_waitcnt lgkmcnt(4)
	v_cvt_pk_bf16_f32 v1, v9, v10
	s_waitcnt lgkmcnt(2)
	v_cvt_pk_bf16_f32 v2, v11, v12
	s_waitcnt lgkmcnt(0)
	v_cvt_pk_bf16_f32 v3, v13, v14
	ds_read_b32 v7, v6 offset:16448
	ds_read_b32 v8, v6 offset:17476
	ds_read_b32 v9, v6 offset:18504
	ds_read_b32 v10, v6 offset:19532
	ds_read_b32 v11, v6 offset:20560
	ds_read_b32 v12, v6 offset:21588
	ds_read_b32 v13, v6 offset:22616
	ds_read_b32 v14, v6 offset:23644
	global_store_dwordx4 v[4:5], v[0:3], off offset:16
	s_waitcnt lgkmcnt(6)
	s_nop 0
	v_cvt_pk_bf16_f32 v0, v7, v8
	s_waitcnt lgkmcnt(4)
	v_cvt_pk_bf16_f32 v1, v9, v10
	s_waitcnt lgkmcnt(2)
	v_cvt_pk_bf16_f32 v2, v11, v12
	s_waitcnt lgkmcnt(0)
	v_cvt_pk_bf16_f32 v3, v13, v14
	ds_read_b32 v7, v6 offset:24672
	ds_read_b32 v8, v6 offset:25700
	ds_read_b32 v9, v6 offset:26728
	ds_read_b32 v10, v6 offset:27756
	ds_read_b32 v11, v6 offset:28784
	ds_read_b32 v12, v6 offset:29812
	ds_read_b32 v13, v6 offset:30840
	ds_read_b32 v6, v6 offset:31868
	global_store_dwordx4 v[4:5], v[0:3], off offset:32
	s_waitcnt lgkmcnt(6)
	s_nop 0
	v_cvt_pk_bf16_f32 v0, v7, v8
	s_waitcnt lgkmcnt(4)
	v_cvt_pk_bf16_f32 v1, v9, v10
	s_waitcnt lgkmcnt(2)
	v_cvt_pk_bf16_f32 v2, v11, v12
	s_waitcnt lgkmcnt(0)
	v_cvt_pk_bf16_f32 v3, v13, v6
	global_store_dwordx4 v[4:5], v[0:3], off offset:48
	s_barrier

; DI u32x4 pack8(const float* o) { u32x4 r; r.x = pk2(o[0], o[1]); r.y = pk2(o[2], o[3]); r.z = pk2(o[4], o[5]); r.w = pk2(o[6], o[7]); return r; }
; DI int otid() { int t = threadIdx.x; asm volatile("" : "+v"(t)); return t; }
; DI void transpose_item(const float* src, int ld, int srcoff, bf16_t* dst, int kt, int nt, unsigned char* smem) {
;     float* tile = (float*)smem;
;     const int tid = otid();
; #pragma unroll
;     for (int i = 0; i < 8; ++i) {
;         const int kr = (tid >> 6) + 8 * i, nc = (tid & 63) * 4;
;         const f32x4 v = __builtin_nontemporal_load((const f32x4*)(src + (size_t)(kt * 64 + kr) * ld + srcoff + nt * 256 + nc));
;         tile[kr * 257 + nc + 0] = v[0]; tile[kr * 257 + nc + 1] = v[1]; tile[kr * 257 + nc + 2] = v[2]; tile[kr * 257 + nc + 3] = v[3];
;     }
;     __syncthreads();
;     {
;         const int n = tid >> 1, k0 = (tid & 1) * 32;
; #pragma unroll
;         for (int k8 = 0; k8 < 4; ++k8) {
;             float o[8];
; #pragma unroll
;             for (int j = 0; j < 8; ++j) o[j] = tile[(k0 + 8 * k8 + j) * 257 + n];
;             *(u32x4*)(dst + (size_t)(nt * 256 + n) * 2048 + kt * 64 + k0 + 8 * k8) = pack8(o);
;         }
;     }
;     __syncthreads();
; }
; DI void weight_prep_item(const P& q, int l, int it, unsigned char* sm) {
;     ...
;     else if (it < 96 + 896 + 256) { const int r = it - 96 - 896, kt = r / 8, nt = r % 8;
;         transpose_item(q.w_out + (size_t)l * DM * DM, DM, 0, (bf16_t*)(q.ws + WS_WOUTT) + (size_t)l * DM * DM, kt, nt, sm); }
; __global__ __launch_bounds__(512, 2) void mega(P p) {
;     ...
;                 } else post_phase(q, 0, sm, 0, NLAT / 16, b1 - 32, nb - 32);
.Lpost0_retA:
	v_readlane_b32 s98, v253, 0
	v_readlane_b32 s0, v254, 26
	v_readlane_b32 s1, v254, 27
	s_mov_b64 s[2:3], 0
	v_readlane_b32 s4, v252, 16
	v_readlane_b32 s5, v252, 17
	s_add_u32 s98, s98, 0x360
	v_lshrrev_b32_e32 v85, 6, v166
	v_and_b32_e32 v82, 63, v166
	v_mul_u32_u24_e32 v80, 0x70c0, v85
	v_lshlrev_b32_e32 v81, 13, v85
	v_lshl_add_u32 v80, v82, 4, v80
	v_lshl_add_u32 v81, v82, 4, v81
	v_mul_u32_u24_e32 v85, 0x404, v85
	v_lshl_add_u32 v82, v82, 4, v85
	v_add_u32_e32 v86, 0x0, v82
	v_add_u32_e32 v87, 0x2020, v82
	v_add_u32_e32 v88, 0x4040, v82
	v_add_u32_e32 v89, 0x6060, v82
	v_add_u32_e32 v90, 0x8080, v82
	v_add_u32_e32 v91, 0xa0a0, v82
	v_add_u32_e32 v92, 0xc0c0, v82
	v_add_u32_e32 v93, 0xe0e0, v82
	v_lshrrev_b32_e32 v85, 1, v166
	v_and_b32_e32 v84, 1, v166
	v_mul_u32_u24_e32 v83, 0x8080, v84
	v_lshl_add_u32 v83, v85, 2, v83
	v_lshlrev_b32_e32 v84, 6, v84
	v_lshl_add_u32 v84, v85, 12, v84
	s_cmp_lt_u32 s98, 0x480
	s_cbranch_scc0 .Ldefw_done
.Ldefw_item:
	s_cmp_lt_u32 s98, 0x380
	s_cbranch_scc0 .Ldefw_wout
	s_mul_i32 s24, s98, 0x925
	s_lshr_b32 s24, s24, 16
	s_mul_i32 s27, s24, 28
	s_sub_u32 s27, s98, s27
	s_cmp_lt_u32 s27, 4
	s_cselect_b32 s28, 0, 32
	s_cmp_lt_u32 s27, 12
	s_cselect_b32 s28, s28, 48
	s_lshl_b32 s30, s27, 8
	s_add_u32 s28, s28, s30
	s_lshl_b32 s28, s28, 2
	s_mul_i32 s30, s24, 0x1c3000
	s_add_u32 s28, s28, s30
	s_add_u32 s28, s28, 0x3860000
	s_add_u32 s42, s2, s28
	s_addc_u32 s43, s3, 0
	s_mov_b32 s26, 0x38600
	s_lshl_b32 s30, s27, 20
	s_lshl_b32 s31, s24, 7
	s_add_u32 s30, s30, s31
	s_add_u32 s30, s30, 0x1c00000
	s_add_u32 s44, s0, s30
	s_addc_u32 s45, s1, 0
	v_mov_b32_e32 v85, v80
	s_branch .Ldefw_go
.Ldefw_wout:
	s_sub_u32 s24, s98, 0x380
	s_and_b32 s27, s24, 7
	s_lshr_b32 s24, s24, 3
	s_lshl_b32 s28, s27, 10
	s_lshl_b32 s30, s24, 19
	s_add_u32 s28, s28, s30
	s_add_u32 s28, s28, 0x1000000
	s_add_u32 s42, s4, s28
	s_addc_u32 s43, s5, 0
	s_mov_b32 s26, 0x10000
	s_lshl_b32 s30, s27, 20
	s_lshl_b32 s31, s24, 7
	s_add_u32 s30, s30, s31
	s_add_u32 s30, s30, 0x4000000
	s_add_u32 s44, s0, s30
	s_addc_u32 s45, s1, 0
	v_mov_b32_e32 v85, v81
.Ldefw_go:
	global_load_dwordx4 v[0:3], v85, s[42:43] nt
	s_add_u32 s42, s42, s26
	s_addc_u32 s43, s43, 0
	global_load_dwordx4 v[4:7], v85, s[42:43] nt
	s_add_u32 s42, s42, s26
	s_addc_u32 s43, s43, 0
	global_load_dwordx4 v[8:11], v85, s[42:43] nt
	s_add_u32 s42, s42, s26
	s_addc_u32 s43, s43, 0
	global_load_dwordx4 v[12:15], v85, s[42:43] nt
	s_add_u32 s42, s42, s26
	s_addc_u32 s43, s43, 0
	global_load_dwordx4 v[16:19], v85, s[42:43] nt
	s_add_u32 s42, s42, s26
	s_addc_u32 s43, s43, 0
	global_load_dwordx4 v[20:23], v85, s[42:43] nt
	s_add_u32 s42, s42, s26
	s_addc_u32 s43, s43, 0
	global_load_dwordx4 v[24:27], v85, s[42:43] nt
	s_add_u32 s42, s42, s26
	s_addc_u32 s43, s43, 0
	global_load_dwordx4 v[28:31], v85, s[42:43] nt
	s_waitcnt vmcnt(7)
	ds_write2_b32 v86, v0, v1 offset1:1
	ds_write2_b32 v86, v2, v3 offset0:2 offset1:3
	s_waitcnt vmcnt(6)
	ds_write2_b32 v87, v4, v5 offset1:1
	ds_write2_b32 v87, v6, v7 offset0:2 offset1:3
	s_waitcnt vmcnt(5)
	ds_write2_b32 v88, v8, v9 offset1:1
	ds_write2_b32 v88, v10, v11 offset0:2 offset1:3
	s_waitcnt vmcnt(4)
	ds_write2_b32 v89, v12, v13 offset1:1
	ds_write2_b32 v89, v14, v15 offset0:2 offset1:3
	s_waitcnt vmcnt(3)
	ds_write2_b32 v90, v16, v17 offset1:1
	ds_write2_b32 v90, v18, v19 offset0:2 offset1:3
	s_waitcnt vmcnt(2)
	ds_write2_b32 v91, v20, v21 offset1:1
	ds_write2_b32 v91, v22, v23 offset0:2 offset1:3
	s_waitcnt vmcnt(1)
	ds_write2_b32 v92, v24, v25 offset1:1
	ds_write2_b32 v92, v26, v27 offset0:2 offset1:3
	s_waitcnt vmcnt(0)
	ds_write2_b32 v93, v28, v29 offset1:1
	ds_write2_b32 v93, v30, v31 offset0:2 offset1:3
	s_waitcnt lgkmcnt(0)
	s_barrier
	ds_read_b32 v32, v83 offset:0
	ds_read_b32 v33, v83 offset:1028
	ds_read_b32 v34, v83 offset:2056
	ds_read_b32 v35, v83 offset:3084
	ds_read_b32 v36, v83 offset:4112
	ds_read_b32 v37, v83 offset:5140
	ds_read_b32 v38, v83 offset:6168
	ds_read_b32 v39, v83 offset:7196
	ds_read_b32 v40, v83 offset:8224
	ds_read_b32 v41, v83 offset:9252
	ds_read_b32 v42, v83 offset:10280
	ds_read_b32 v43, v83 offset:11308
	ds_read_b32 v44, v83 offset:12336
	ds_read_b32 v45, v83 offset:13364
	ds_read_b32 v46, v83 offset:14392
	s_waitcnt lgkmcnt(7)
	ds_read_b32 v47, v83 offset:15420
	v_cvt_pk_bf16_f32 v64, v32, v33
	v_cvt_pk_bf16_f32 v65, v34, v35
	v_cvt_pk_bf16_f32 v66, v36, v37
	v_cvt_pk_bf16_f32 v67, v38, v39
	global_store_dwordx4 v84, v[64:67], s[44:45] offset:0
	ds_read_b32 v48, v83 offset:16448
	ds_read_b32 v49, v83 offset:17476
	ds_read_b32 v50, v83 offset:18504
	ds_read_b32 v51, v83 offset:19532
	ds_read_b32 v52, v83 offset:20560
	ds_read_b32 v53, v83 offset:21588
	ds_read_b32 v54, v83 offset:22616
	s_waitcnt lgkmcnt(7)
	ds_read_b32 v55, v83 offset:23644
	v_cvt_pk_bf16_f32 v68, v40, v41
	v_cvt_pk_bf16_f32 v69, v42, v43
	v_cvt_pk_bf16_f32 v70, v44, v45
	v_cvt_pk_bf16_f32 v71, v46, v47
	global_store_dwordx4 v84, v[68:71], s[44:45] offset:16
	ds_read_b32 v56, v83 offset:24672
	ds_read_b32 v57, v83 offset:25700
	ds_read_b32 v58, v83 offset:26728
	ds_read_b32 v59, v83 offset:27756
	ds_read_b32 v60, v83 offset:28784
	ds_read_b32 v61, v83 offset:29812
	ds_read_b32 v62, v83 offset:30840
	s_waitcnt lgkmcnt(7)
	ds_read_b32 v63, v83 offset:31868
	v_cvt_pk_bf16_f32 v72, v48, v49
	v_cvt_pk_bf16_f32 v73, v50, v51
	v_cvt_pk_bf16_f32 v74, v52, v53
	v_cvt_pk_bf16_f32 v75, v54, v55
	global_store_dwordx4 v84, v[72:75], s[44:45] offset:32
	s_waitcnt lgkmcnt(0)
	v_cvt_pk_bf16_f32 v76, v56, v57
	v_cvt_pk_bf16_f32 v77, v58, v59
	v_cvt_pk_bf16_f32 v78, v60, v61
	v_cvt_pk_bf16_f32 v79, v62, v63
	global_store_dwordx4 v84, v[76:79], s[44:45] offset:48
	s_add_u32 s98, s98, 0xe0
	s_barrier
	s_cmp_lt_u32 s98, 0x480
	s_cbranch_scc1 .Ldefw_item
